# P11: LayerNorm stats load moved from the k-loop preheader into the peeled last k-iteration (the loop's first counted wait no longer exposes its latency)
# speedup vs baseline: 1.0115x; 1.0010x over previous
; #define PG8_STAGE(bufoff, gbase, voff) do { _Pragma("unroll") for (int _i = 0; _i < 2; ++_i) \
;         __builtin_amdgcn_global_load_lds((const unsigned*)((const char*)(gbase) + (voff)[_i]), (PG8_LAS unsigned*)(lds + (bufoff) + ldsw + _i * 8192), 16, 0, 0); } while (0)
; #define PG8_LDA(dst, b, h) do { _Pragma("unroll") for (int m = 0; m < 4; ++m) _Pragma("unroll") for (int k = 0; k < 2; ++k) dst[m][k] = *(const PG8_LAS bf16x8*)(lds + PG8_SA(b, h) + aoff + m * 2048 + k * 1024); } while (0)
; #define PG8_LDB(dst, b, h) do { _Pragma("unroll") for (int n = 0; n < 2; ++n) _Pragma("unroll") for (int k = 0; k < 2; ++k) dst[n][k] = *(const PG8_LAS bf16x8*)(lds + PG8_SB(b, h) + boff + n * 2048 + k * 1024); } while (0)
; #define PG8_WAIT_V(n) asm volatile("s_waitcnt vmcnt(" #n ")" ::: "memory")
; #define PG8_WAIT_L(n) asm volatile("s_waitcnt lgkmcnt(" #n ")" ::: "memory")
; template <class Epi, class Sched, bool ALIGN_EPI = false, bool SP2 = false>
; __device__ __forceinline__ void gemm_phase(PG8_LAS unsigned char* lds, const Gemm g, const Sched& S, const Epi& E) {
;     ...
;     for (;;) {
;         const bool has_next = S.next(ui + 1, nxt);
;         const char* nA = has_next ? (const char*)g.A + (size_t)nxt.pm * tstepA + (size_t)((nxt.pn >> g.a_shift) * g.a_stride) : cA; const char* nB = has_next ? (const char*)g.Bt + (size_t)nxt.pn * tstepB : cB;
; #pragma clang loop unroll(disable)
;         for (int t = 0; t < nt; t += 2) {
;             const bool last = (t == nt - 2);
;             const char* a1 = cA + (size_t)(t + 1) * kstep;
;             const char* a2 = last ? nA : cA + (size_t)(t + 2) * kstep; const char* b2 = last ? nB : cB + (size_t)(t + 2) * kstep;
;             const char* a3 = a2 + kstep; const char* b3 = b2 + kstep;
;             if (last && has_next) S.a_ready(nxt);
;             if constexpr (SP2) {
;             PG8_LDB(B0, 0, 0); PG8_LDB(B1, 0, 1); PG8_SCHED; PG8_LDA(At, 0, 0); PG8_STAGE(PG8_SA(1, 1), a1 + hstepA, voffA);
;             PG8_WAIT_V(8); PG8_WAIT_L(0); PG8_BAR; PG8_MMA(0, 0, At, B0); PG8_MMA(0, 1, At, B1); PG8_BAR; PG8_SCHED;
;     ...
; #pragma unroll
;         for (int a = 0; a < 2; ++a)
; #pragma unroll
;             for (int b = 0; b < 2; ++b)
; #pragma unroll
;                 for (int m = 0; m < 4; ++m)
; #pragma unroll
;                     for (int n = 0; n < 2; ++n) acc[a][b][m][n] = (f32x4){0.f, 0.f, 0.f, 0.f};
.LBB0_1126:
	s_ashr_i32 s25, s24, 31
	s_lshl_b64 s[26:27], s[24:25], 21
	s_add_u32 s36, s54, s26
	s_addc_u32 s37, s55, s27
	s_and_b64 s[26:27], s[4:5], exec
	s_cselect_b32 s25, s37, s41
	s_cselect_b32 s26, s36, s40
	s_ashr_i32 s23, s22, 31
	s_lshl_b64 s[34:35], s[22:23], 21
	s_add_u32 s38, s19, s34
	s_addc_u32 s39, s21, s35
	s_and_b64 s[34:35], s[4:5], exec
	s_cselect_b32 s23, s39, s43
	s_cselect_b32 s27, s38, s42
	s_add_u32 s40, s40, 0x100080
	s_addc_u32 s41, s41, 0
	s_add_u32 s45, s42, 0x100
	v_mov_b32_e32 v2, 0
	s_addc_u32 s52, s43, 0
	s_mov_b32 s53, -2
	v_mov_b32_e32 v3, v2
	v_mov_b64_e32 v[4:5], 0
	v_mov_b64_e32 v[14:15], 0
	v_mov_b64_e32 v[16:17], 0
	v_mov_b64_e32 v[18:19], 0
	v_mov_b64_e32 v[20:21], 0
	v_mov_b64_e32 v[30:31], 0
	v_mov_b64_e32 v[32:33], 0
	v_mov_b64_e32 v[34:35], 0
	v_mov_b64_e32 v[36:37], 0
	v_mov_b64_e32 v[46:47], 0
	v_mov_b64_e32 v[48:49], 0
	v_mov_b64_e32 v[50:51], 0
	v_mov_b64_e32 v[52:53], 0
	v_mov_b64_e32 v[62:63], 0
	v_mov_b64_e32 v[64:65], 0
	v_mov_b64_e32 v[6:7], 0
	v_mov_b64_e32 v[8:9], 0
	v_mov_b64_e32 v[10:11], 0
	v_mov_b64_e32 v[12:13], 0
	v_mov_b64_e32 v[22:23], 0
	v_mov_b64_e32 v[24:25], 0
	v_mov_b64_e32 v[26:27], 0
	v_mov_b64_e32 v[28:29], 0
	v_mov_b64_e32 v[38:39], 0
	v_mov_b64_e32 v[40:41], 0
	v_mov_b64_e32 v[42:43], 0
	v_mov_b64_e32 v[44:45], 0
	v_mov_b64_e32 v[54:55], 0
	v_mov_b64_e32 v[56:57], 0
	v_mov_b64_e32 v[58:59], 0
	v_mov_b64_e32 v[60:61], 0
	v_mov_b64_e32 v[66:67], 0
	v_mov_b64_e32 v[68:69], 0
	v_mov_b64_e32 v[78:79], 0
	v_mov_b64_e32 v[80:81], 0
	v_mov_b64_e32 v[82:83], 0
	v_mov_b64_e32 v[84:85], 0
	v_mov_b64_e32 v[94:95], 0
	v_mov_b64_e32 v[96:97], 0
	v_mov_b64_e32 v[98:99], 0
	v_mov_b64_e32 v[100:101], 0
	v_mov_b64_e32 v[110:111], 0
	v_mov_b64_e32 v[112:113], 0
	v_mov_b64_e32 v[114:115], 0
	v_mov_b64_e32 v[116:117], 0
	v_mov_b64_e32 v[126:127], 0
	v_mov_b64_e32 v[128:129], 0
	v_mov_b64_e32 v[70:71], 0
	v_mov_b64_e32 v[72:73], 0
	v_mov_b64_e32 v[74:75], 0
	v_mov_b64_e32 v[76:77], 0
	v_mov_b64_e32 v[86:87], 0
	v_mov_b64_e32 v[88:89], 0
	v_mov_b64_e32 v[90:91], 0
	v_mov_b64_e32 v[92:93], 0
	v_mov_b64_e32 v[102:103], 0
	v_mov_b64_e32 v[104:105], 0
	v_mov_b64_e32 v[106:107], 0
	v_mov_b64_e32 v[108:109], 0
	v_mov_b64_e32 v[118:119], 0
	v_mov_b64_e32 v[120:121], 0
	v_mov_b64_e32 v[122:123], 0
	v_mov_b64_e32 v[124:125], 0
	s_setprio 1
	s_cmp_eq_u64 s[14:15], 0
	s_cbranch_scc1 .Lsp_LBB0_1127
	s_setprio 0
.Lsp_LBB0_1127:
.LBB0_1127:
	ds_read_b128 v[130:133], v203
	ds_read_b128 v[134:137], v203 offset:1024
	ds_read_b128 v[138:141], v203 offset:2048
	ds_read_b128 v[142:145], v203 offset:3072
	ds_read_b128 v[146:149], v205
	ds_read_b128 v[150:153], v205 offset:1024
	ds_read_b128 v[154:157], v205 offset:2048
	ds_read_b128 v[158:161], v205 offset:3072
	s_add_u32 s34, s40, 0xfff00080
	s_addc_u32 s35, s41, -1
	s_cmp_eq_u32 s53, 60
	s_cselect_b32 s35, s25, s35
	s_cselect_b32 s34, s26, s34
	s_cselect_b32 s43, s23, s52
	s_cselect_b32 s42, s27, s45
	s_add_i32 m0, s47, 0xc000
	ds_read_b128 v[162:165], v207
	ds_read_b128 v[166:169], v207 offset:1024
	ds_read_b128 v[170:173], v207 offset:2048
	ds_read_b128 v[174:177], v207 offset:3072
	ds_read_b128 v[196:199], v207 offset:4096
	ds_read_b128 v[208:211], v207 offset:5120
	ds_read_b128 v[212:215], v207 offset:6144
	ds_read_b128 v[216:219], v207 offset:7168
	global_load_lds_dwordx4 v188, s[40:41]
	s_add_i32 m0, s47, 0xe000
	s_nop 0
	global_load_lds_dwordx4 v190, s[40:41]
	s_waitcnt vmcnt(8)
	s_waitcnt lgkmcnt(0)
	s_barrier
	s_waitcnt lgkmcnt(0)
	v_mfma_f32_16x16x32_bf16 v[122:125], v[130:133], v[162:165], v[122:125]
	v_mfma_f32_16x16x32_bf16 v[118:121], v[138:141], v[162:165], v[118:121]
	v_mfma_f32_16x16x32_bf16 v[106:109], v[130:133], v[170:173], v[106:109]
	v_mfma_f32_16x16x32_bf16 v[102:105], v[138:141], v[170:173], v[102:105]
	v_mfma_f32_16x16x32_bf16 v[90:93], v[130:133], v[196:199], v[90:93]
	v_mfma_f32_16x16x32_bf16 v[86:89], v[138:141], v[196:199], v[86:89]
	v_mfma_f32_16x16x32_bf16 v[74:77], v[130:133], v[212:215], v[74:77]
	v_mfma_f32_16x16x32_bf16 v[70:73], v[138:141], v[212:215], v[70:73]
	v_mfma_f32_16x16x32_bf16 v[122:125], v[134:137], v[166:169], v[122:125]
	v_mfma_f32_16x16x32_bf16 v[118:121], v[142:145], v[166:169], v[118:121]
	v_mfma_f32_16x16x32_bf16 v[106:109], v[134:137], v[174:177], v[106:109]
	v_mfma_f32_16x16x32_bf16 v[102:105], v[142:145], v[174:177], v[102:105]
	v_mfma_f32_16x16x32_bf16 v[90:93], v[134:137], v[208:211], v[90:93]
	v_mfma_f32_16x16x32_bf16 v[86:89], v[142:145], v[208:211], v[86:89]
	v_mfma_f32_16x16x32_bf16 v[74:77], v[134:137], v[216:219], v[74:77]
	v_mfma_f32_16x16x32_bf16 v[70:73], v[142:145], v[216:219], v[70:73]
	v_mfma_f32_16x16x32_bf16 v[126:129], v[146:149], v[162:165], v[126:129]
	v_mfma_f32_16x16x32_bf16 v[114:117], v[154:157], v[162:165], v[114:117]
	v_mfma_f32_16x16x32_bf16 v[110:113], v[146:149], v[170:173], v[110:113]
	v_mfma_f32_16x16x32_bf16 v[98:101], v[154:157], v[170:173], v[98:101]
	v_mfma_f32_16x16x32_bf16 v[94:97], v[146:149], v[196:199], v[94:97]
	v_mfma_f32_16x16x32_bf16 v[82:85], v[154:157], v[196:199], v[82:85]
	v_mfma_f32_16x16x32_bf16 v[78:81], v[146:149], v[212:215], v[78:81]
	v_mfma_f32_16x16x32_bf16 v[66:69], v[154:157], v[212:215], v[66:69]
	v_mfma_f32_16x16x32_bf16 v[126:129], v[150:153], v[166:169], v[126:129]
	v_mfma_f32_16x16x32_bf16 v[114:117], v[158:161], v[166:169], v[114:117]
	v_mfma_f32_16x16x32_bf16 v[110:113], v[150:153], v[174:177], v[110:113]
	v_mfma_f32_16x16x32_bf16 v[98:101], v[158:161], v[174:177], v[98:101]
	v_mfma_f32_16x16x32_bf16 v[94:97], v[150:153], v[208:211], v[94:97]
	v_mfma_f32_16x16x32_bf16 v[82:85], v[158:161], v[208:211], v[82:85]
	v_mfma_f32_16x16x32_bf16 v[78:81], v[150:153], v[216:219], v[78:81]
	v_mfma_f32_16x16x32_bf16 v[66:69], v[158:161], v[216:219], v[66:69]
	s_barrier
; #define PG8_STAGE(bufoff, gbase, voff) do { _Pragma("unroll") for (int _i = 0; _i < 2; ++_i) \
;         __builtin_amdgcn_global_load_lds((const unsigned*)((const char*)(gbase) + (voff)[_i]), (PG8_LAS unsigned*)(lds + (bufoff) + ldsw + _i * 8192), 16, 0, 0); } while (0)
; #define PG8_LDA(dst, b, h) do { _Pragma("unroll") for (int m = 0; m < 4; ++m) _Pragma("unroll") for (int k = 0; k < 2; ++k) dst[m][k] = *(const PG8_LAS bf16x8*)(lds + PG8_SA(b, h) + aoff + m * 2048 + k * 1024); } while (0)
; #define PG8_LDB(dst, b, h) do { _Pragma("unroll") for (int n = 0; n < 2; ++n) _Pragma("unroll") for (int k = 0; k < 2; ++k) dst[n][k] = *(const PG8_LAS bf16x8*)(lds + PG8_SB(b, h) + boff + n * 2048 + k * 1024); } while (0)
; #define PG8_MMA(ai, bj, At, Bt) do { __builtin_amdgcn_s_setprio(1); _Pragma("unroll") for (int m = 0; m < 4; ++m) _Pragma("unroll") for (int n = 0; n < 2; ++n) _Pragma("unroll") for (int k = 0; k < 2; ++k) \
;         acc[ai][bj][m][n] = __builtin_amdgcn_mfma_f32_16x16x32_bf16(Bt[n][k], At[m][k], acc[ai][bj][m][n], 0, 0, 0); __builtin_amdgcn_s_setprio(0); } while (0)
; #define PG8_WAIT_V(n) asm volatile("s_waitcnt vmcnt(" #n ")" ::: "memory")
; #define PG8_WAIT_L(n) asm volatile("s_waitcnt lgkmcnt(" #n ")" ::: "memory")
; #define PG8_BAR __builtin_amdgcn_s_barrier()
; #define PG8_SCHED __builtin_amdgcn_sched_barrier(0)
; template <class Epi, class Sched, bool ALIGN_EPI = false, bool SP2 = false>
; __device__ __forceinline__ void gemm_phase(PG8_LAS unsigned char* lds, const Gemm g, const Sched& S, const Epi& E) {
;     ...
;             PG8_LDA(At, 0, 1); PG8_STAGE(PG8_SB(0, 0), b2, voffB); PG8_STAGE(PG8_SB(0, 1), b2 + hstepB, voffB); PG8_STAGE(PG8_SA(0, 0), a2, voffA);
;             PG8_WAIT_V(8); PG8_WAIT_L(0); PG8_BAR; PG8_MMA(1, 0, At, B0); PG8_MMA(1, 1, At, B1); PG8_BAR; PG8_SCHED;
;             PG8_LDB(B0, 1, 0); PG8_LDB(B1, 1, 1); PG8_SCHED; PG8_LDA(At, 1, 0); PG8_STAGE(PG8_SA(0, 1), a2 + hstepA, voffA);
;             PG8_WAIT_V(8); PG8_WAIT_L(0); PG8_BAR; PG8_MMA(0, 0, At, B0); PG8_MMA(0, 1, At, B1); PG8_BAR; PG8_SCHED;
;             PG8_LDA(At, 1, 1); PG8_STAGE(PG8_SB(1, 0), b3, voffB); PG8_STAGE(PG8_SB(1, 1), b3 + hstepB, voffB); PG8_STAGE(PG8_SA(1, 0), a3, voffA);
;             PG8_WAIT_V(8); PG8_WAIT_L(0); PG8_BAR; PG8_MMA(1, 0, At, B0); PG8_MMA(1, 1, At, B1); PG8_BAR; PG8_SCHED;
	s_add_i32 s73, s68, s17
	s_add_u32 s98, s42, 0x80
	s_addc_u32 s99, s43, 0
	s_add_u32 s100, s34, 0x80
	s_addc_u32 s101, s35, 0
	s_mov_b32 m0, s73
	ds_read_b128 v[162:165], v207 offset:16384
	ds_read_b128 v[166:169], v207 offset:17408
	ds_read_b128 v[170:173], v207 offset:18432
	ds_read_b128 v[174:177], v207 offset:19456
	ds_read_b128 v[196:199], v207 offset:20480
	ds_read_b128 v[208:211], v207 offset:21504
	ds_read_b128 v[212:215], v207 offset:22528
	ds_read_b128 v[216:219], v207 offset:23552
	global_load_lds_dwordx4 v182, s[42:43]
	s_add_i32 m0, s73, 0x2000
	s_add_u32 s74, s42, 0x100000
	s_addc_u32 s75, s43, 0
	s_add_i32 s73, s69, s17
	global_load_lds_dwordx4 v178, s[42:43]
	s_mov_b32 m0, s73
	s_nop 0
	global_load_lds_dwordx4 v182, s[74:75]
	s_add_i32 m0, s73, 0x2000
	s_nop 0
	global_load_lds_dwordx4 v178, s[74:75]
	s_mov_b32 m0, s47
	s_nop 0
	global_load_lds_dwordx4 v184, s[34:35]
	s_mov_b32 m0, s48
	s_nop 0
	global_load_lds_dwordx4 v180, s[34:35]
	s_waitcnt vmcnt(8)
	s_waitcnt lgkmcnt(0)
	s_barrier
	s_waitcnt lgkmcnt(0)
	v_mfma_f32_16x16x32_bf16 v[58:61], v[130:133], v[162:165], v[58:61]
	v_mfma_f32_16x16x32_bf16 v[54:57], v[138:141], v[162:165], v[54:57]
	v_mfma_f32_16x16x32_bf16 v[42:45], v[130:133], v[170:173], v[42:45]
	v_mfma_f32_16x16x32_bf16 v[38:41], v[138:141], v[170:173], v[38:41]
	v_mfma_f32_16x16x32_bf16 v[26:29], v[130:133], v[196:199], v[26:29]
	v_mfma_f32_16x16x32_bf16 v[22:25], v[138:141], v[196:199], v[22:25]
	v_mfma_f32_16x16x32_bf16 v[10:13], v[130:133], v[212:215], v[10:13]
	v_mfma_f32_16x16x32_bf16 v[6:9], v[138:141], v[212:215], v[6:9]
	v_mfma_f32_16x16x32_bf16 v[58:61], v[134:137], v[166:169], v[58:61]
	v_mfma_f32_16x16x32_bf16 v[54:57], v[142:145], v[166:169], v[54:57]
	v_mfma_f32_16x16x32_bf16 v[42:45], v[134:137], v[174:177], v[42:45]
	v_mfma_f32_16x16x32_bf16 v[38:41], v[142:145], v[174:177], v[38:41]
	v_mfma_f32_16x16x32_bf16 v[26:29], v[134:137], v[208:211], v[26:29]
	v_mfma_f32_16x16x32_bf16 v[22:25], v[142:145], v[208:211], v[22:25]
	v_mfma_f32_16x16x32_bf16 v[10:13], v[134:137], v[216:219], v[10:13]
	v_mfma_f32_16x16x32_bf16 v[6:9], v[142:145], v[216:219], v[6:9]
	v_mfma_f32_16x16x32_bf16 v[62:65], v[146:149], v[162:165], v[62:65]
	v_mfma_f32_16x16x32_bf16 v[50:53], v[154:157], v[162:165], v[50:53]
	v_mfma_f32_16x16x32_bf16 v[46:49], v[146:149], v[170:173], v[46:49]
	v_mfma_f32_16x16x32_bf16 v[34:37], v[154:157], v[170:173], v[34:37]
	v_mfma_f32_16x16x32_bf16 v[30:33], v[146:149], v[196:199], v[30:33]
	v_mfma_f32_16x16x32_bf16 v[18:21], v[154:157], v[196:199], v[18:21]
	v_mfma_f32_16x16x32_bf16 v[14:17], v[146:149], v[212:215], v[14:17]
	v_mfma_f32_16x16x32_bf16 v[2:5], v[154:157], v[212:215], v[2:5]
	v_mfma_f32_16x16x32_bf16 v[62:65], v[150:153], v[166:169], v[62:65]
	v_mfma_f32_16x16x32_bf16 v[50:53], v[158:161], v[166:169], v[50:53]
	v_mfma_f32_16x16x32_bf16 v[46:49], v[150:153], v[174:177], v[46:49]
	v_mfma_f32_16x16x32_bf16 v[34:37], v[158:161], v[174:177], v[34:37]
	v_mfma_f32_16x16x32_bf16 v[30:33], v[150:153], v[208:211], v[30:33]
	v_mfma_f32_16x16x32_bf16 v[18:21], v[158:161], v[208:211], v[18:21]
	v_mfma_f32_16x16x32_bf16 v[14:17], v[150:153], v[216:219], v[14:17]
	v_mfma_f32_16x16x32_bf16 v[2:5], v[158:161], v[216:219], v[2:5]
	s_barrier
	s_add_i32 s73, 0, 0x18000
	s_add_i32 s74, 0, 0x1c000
	v_add_u32_e32 v142, s73, v1
	v_add_u32_e32 v158, s74, v1
	ds_read_b128 v[130:133], v142
	ds_read_b128 v[134:137], v142 offset:1024
	ds_read_b128 v[138:141], v142 offset:2048
	ds_read_b128 v[142:145], v142 offset:3072
	ds_read_b128 v[146:149], v158
	ds_read_b128 v[150:153], v158 offset:1024
	ds_read_b128 v[154:157], v158 offset:2048
	ds_read_b128 v[158:161], v158 offset:3072
	s_add_u32 s34, s34, 0x100000
	s_addc_u32 s35, s35, 0
	s_mov_b32 m0, s49
	ds_read_b128 v[162:165], v207 offset:32768
	ds_read_b128 v[166:169], v207 offset:33792
	ds_read_b128 v[170:173], v207 offset:34816
	ds_read_b128 v[174:177], v207 offset:35840
	ds_read_b128 v[196:199], v207 offset:36864
	ds_read_b128 v[208:211], v207 offset:37888
	ds_read_b128 v[212:215], v207 offset:38912
	ds_read_b128 v[216:219], v207 offset:39936
	global_load_lds_dwordx4 v184, s[34:35]
	s_mov_b32 m0, s60
	s_nop 0
	global_load_lds_dwordx4 v180, s[34:35]
	s_waitcnt vmcnt(8)
	s_waitcnt lgkmcnt(0)
	s_barrier
	s_waitcnt lgkmcnt(0)
	v_mfma_f32_16x16x32_bf16 v[122:125], v[130:133], v[162:165], v[122:125]
	v_mfma_f32_16x16x32_bf16 v[118:121], v[138:141], v[162:165], v[118:121]
	v_mfma_f32_16x16x32_bf16 v[106:109], v[130:133], v[170:173], v[106:109]
	v_mfma_f32_16x16x32_bf16 v[102:105], v[138:141], v[170:173], v[102:105]
	v_mfma_f32_16x16x32_bf16 v[90:93], v[130:133], v[196:199], v[90:93]
	v_mfma_f32_16x16x32_bf16 v[86:89], v[138:141], v[196:199], v[86:89]
	v_mfma_f32_16x16x32_bf16 v[74:77], v[130:133], v[212:215], v[74:77]
	v_mfma_f32_16x16x32_bf16 v[70:73], v[138:141], v[212:215], v[70:73]
	v_mfma_f32_16x16x32_bf16 v[122:125], v[134:137], v[166:169], v[122:125]
	v_mfma_f32_16x16x32_bf16 v[118:121], v[142:145], v[166:169], v[118:121]
	v_mfma_f32_16x16x32_bf16 v[106:109], v[134:137], v[174:177], v[106:109]
	v_mfma_f32_16x16x32_bf16 v[102:105], v[142:145], v[174:177], v[102:105]
	v_mfma_f32_16x16x32_bf16 v[90:93], v[134:137], v[208:211], v[90:93]
	v_mfma_f32_16x16x32_bf16 v[86:89], v[142:145], v[208:211], v[86:89]
	v_mfma_f32_16x16x32_bf16 v[74:77], v[134:137], v[216:219], v[74:77]
	v_mfma_f32_16x16x32_bf16 v[70:73], v[142:145], v[216:219], v[70:73]
	v_mfma_f32_16x16x32_bf16 v[126:129], v[146:149], v[162:165], v[126:129]
	v_mfma_f32_16x16x32_bf16 v[114:117], v[154:157], v[162:165], v[114:117]
	v_mfma_f32_16x16x32_bf16 v[110:113], v[146:149], v[170:173], v[110:113]
	v_mfma_f32_16x16x32_bf16 v[98:101], v[154:157], v[170:173], v[98:101]
	v_mfma_f32_16x16x32_bf16 v[94:97], v[146:149], v[196:199], v[94:97]
	v_mfma_f32_16x16x32_bf16 v[82:85], v[154:157], v[196:199], v[82:85]
	v_mfma_f32_16x16x32_bf16 v[78:81], v[146:149], v[212:215], v[78:81]
	v_mfma_f32_16x16x32_bf16 v[66:69], v[154:157], v[212:215], v[66:69]
	v_mfma_f32_16x16x32_bf16 v[126:129], v[150:153], v[166:169], v[126:129]
	v_mfma_f32_16x16x32_bf16 v[114:117], v[158:161], v[166:169], v[114:117]
	v_mfma_f32_16x16x32_bf16 v[110:113], v[150:153], v[174:177], v[110:113]
	v_mfma_f32_16x16x32_bf16 v[98:101], v[158:161], v[174:177], v[98:101]
	v_mfma_f32_16x16x32_bf16 v[94:97], v[150:153], v[208:211], v[94:97]
	v_mfma_f32_16x16x32_bf16 v[82:85], v[158:161], v[208:211], v[82:85]
	v_mfma_f32_16x16x32_bf16 v[78:81], v[150:153], v[216:219], v[78:81]
	v_mfma_f32_16x16x32_bf16 v[66:69], v[158:161], v[216:219], v[66:69]
	s_barrier
; #define PG8_STAGE(bufoff, gbase, voff) do { _Pragma("unroll") for (int _i = 0; _i < 2; ++_i) \
;         __builtin_amdgcn_global_load_lds((const unsigned*)((const char*)(gbase) + (voff)[_i]), (PG8_LAS unsigned*)(lds + (bufoff) + ldsw + _i * 8192), 16, 0, 0); } while (0)
; #define PG8_LDA(dst, b, h) do { _Pragma("unroll") for (int m = 0; m < 4; ++m) _Pragma("unroll") for (int k = 0; k < 2; ++k) dst[m][k] = *(const PG8_LAS bf16x8*)(lds + PG8_SA(b, h) + aoff + m * 2048 + k * 1024); } while (0)
; #define PG8_WAIT_V(n) asm volatile("s_waitcnt vmcnt(" #n ")" ::: "memory")
; #define PG8_WAIT_L(n) asm volatile("s_waitcnt lgkmcnt(" #n ")" ::: "memory")
; template <class Epi, class Sched, bool ALIGN_EPI = false, bool SP2 = false>
; __device__ __forceinline__ void gemm_phase(PG8_LAS unsigned char* lds, const Gemm g, const Sched& S, const Epi& E) {
;     ...
;             PG8_LDB(B0, 1, 0); PG8_LDB(B1, 1, 1); PG8_SCHED; PG8_LDA(At, 1, 0); PG8_STAGE(PG8_SA(0, 1), a2 + hstepA, voffA);
;             PG8_WAIT_V(8); PG8_WAIT_L(0); PG8_BAR; PG8_MMA(0, 0, At, B0); PG8_MMA(0, 1, At, B1); PG8_BAR; PG8_SCHED;
;             PG8_LDA(At, 1, 1); PG8_STAGE(PG8_SB(1, 0), b3, voffB); PG8_STAGE(PG8_SB(1, 1), b3 + hstepB, voffB); PG8_STAGE(PG8_SA(1, 0), a3, voffA);
;             PG8_WAIT_V(8); PG8_WAIT_L(0); PG8_BAR; PG8_MMA(1, 0, At, B0); PG8_MMA(1, 1, At, B1); PG8_BAR; PG8_SCHED;
;     __device__ __forceinline__ void operator()(const af4 (&acc)[2][2][4][2], const pg8::Unit& u, int wr_, int wc_, int fr_, int fq_) const {
;         const int tid = my_tid(), lane = tid & 63, wid = __builtin_amdgcn_readfirstlane(tid >> 6), wr = wid >> 2, wc = wid & 3, fr = lane & 15, fq = lane >> 4;
;         (void)wr_; (void)wc_; (void)fr_; (void)fq_;
;         const int chbase = u.pn * 128, grp = u.pn / 6;
;         const bf16* wsg = wsb + (size_t)grp * 128 * 128;
;         const int chl = chbase + 32 * wc + 8 * (fr >> 2) + (fr & 3);
;         float lg[2], lb[2];
; #pragma unroll
;         for (int n = 0; n < 2; ++n) { lg[n] = lng[chl + 4 * n]; lb[n] = lnb[chl + 4 * n]; }
;         v4u raw[2][4];
;         auto load_raw = [&](int ai) {
; #pragma unroll
;             for (int ks = 0; ks < 4; ++ks)
; #pragma unroll
;                 for (int n = 0; n < 2; ++n) raw[n][ks] = *(const GAS v4u*)(VT + (size_t)(chl + 4 * n) * MLAT + u.pm * 256 + ai * 128 + 32 * ks + 8 * fq);
;         };
;         load_raw(0);
	s_add_i32 s34, s73, s17
	s_mov_b32 m0, s34
	ds_read_b128 v[162:165], v207 offset:49152
	ds_read_b128 v[166:169], v207 offset:50176
	ds_read_b128 v[170:173], v207 offset:51200
	ds_read_b128 v[174:177], v207 offset:52224
	ds_read_b128 v[196:199], v207 offset:53248
	ds_read_b128 v[208:211], v207 offset:54272
	ds_read_b128 v[212:215], v207 offset:55296
	ds_read_b128 v[216:219], v207 offset:56320
	global_load_lds_dwordx4 v182, s[98:99]
	s_add_i32 m0, s34, 0x2000
	s_add_u32 s34, s42, 0x100080
	s_addc_u32 s35, s43, 0
	s_add_i32 s42, s74, s17
	global_load_lds_dwordx4 v178, s[98:99]
	s_mov_b32 m0, s42
	s_nop 0
	global_load_lds_dwordx4 v182, s[34:35]
	s_add_i32 m0, s42, 0x2000
	s_nop 0
	global_load_lds_dwordx4 v178, s[34:35]
	s_mov_b32 m0, s64
	s_nop 0
	global_load_lds_dwordx4 v184, s[100:101]
	s_mov_b32 m0, s65
	s_nop 0
	global_load_lds_dwordx4 v180, s[100:101]
	s_waitcnt vmcnt(8)
	s_waitcnt lgkmcnt(0)
	s_barrier
	s_waitcnt lgkmcnt(0)
	v_mfma_f32_16x16x32_bf16 v[58:61], v[130:133], v[162:165], v[58:61]
	v_mfma_f32_16x16x32_bf16 v[54:57], v[138:141], v[162:165], v[54:57]
	v_mfma_f32_16x16x32_bf16 v[42:45], v[130:133], v[170:173], v[42:45]
	v_mfma_f32_16x16x32_bf16 v[38:41], v[138:141], v[170:173], v[38:41]
	v_mfma_f32_16x16x32_bf16 v[26:29], v[130:133], v[196:199], v[26:29]
	v_mfma_f32_16x16x32_bf16 v[22:25], v[138:141], v[196:199], v[22:25]
	v_mfma_f32_16x16x32_bf16 v[10:13], v[130:133], v[212:215], v[10:13]
	v_mfma_f32_16x16x32_bf16 v[6:9], v[138:141], v[212:215], v[6:9]
	v_mfma_f32_16x16x32_bf16 v[58:61], v[134:137], v[166:169], v[58:61]
	v_mfma_f32_16x16x32_bf16 v[54:57], v[142:145], v[166:169], v[54:57]
	v_mfma_f32_16x16x32_bf16 v[42:45], v[134:137], v[174:177], v[42:45]
	v_mfma_f32_16x16x32_bf16 v[38:41], v[142:145], v[174:177], v[38:41]
	v_mfma_f32_16x16x32_bf16 v[26:29], v[134:137], v[208:211], v[26:29]
	v_mfma_f32_16x16x32_bf16 v[22:25], v[142:145], v[208:211], v[22:25]
	v_mfma_f32_16x16x32_bf16 v[10:13], v[134:137], v[216:219], v[10:13]
	v_mfma_f32_16x16x32_bf16 v[6:9], v[142:145], v[216:219], v[6:9]
	v_mfma_f32_16x16x32_bf16 v[62:65], v[146:149], v[162:165], v[62:65]
	v_mfma_f32_16x16x32_bf16 v[50:53], v[154:157], v[162:165], v[50:53]
	v_mfma_f32_16x16x32_bf16 v[46:49], v[146:149], v[170:173], v[46:49]
	v_mfma_f32_16x16x32_bf16 v[34:37], v[154:157], v[170:173], v[34:37]
	v_mfma_f32_16x16x32_bf16 v[30:33], v[146:149], v[196:199], v[30:33]
	v_mfma_f32_16x16x32_bf16 v[18:21], v[154:157], v[196:199], v[18:21]
	v_mfma_f32_16x16x32_bf16 v[14:17], v[146:149], v[212:215], v[14:17]
	v_mfma_f32_16x16x32_bf16 v[2:5], v[154:157], v[212:215], v[2:5]
	v_mfma_f32_16x16x32_bf16 v[62:65], v[150:153], v[166:169], v[62:65]
	v_mfma_f32_16x16x32_bf16 v[50:53], v[158:161], v[166:169], v[50:53]
	v_mfma_f32_16x16x32_bf16 v[46:49], v[150:153], v[174:177], v[46:49]
	v_mfma_f32_16x16x32_bf16 v[34:37], v[158:161], v[174:177], v[34:37]
	v_mfma_f32_16x16x32_bf16 v[30:33], v[150:153], v[208:211], v[30:33]
	v_mfma_f32_16x16x32_bf16 v[18:21], v[158:161], v[208:211], v[18:21]
	v_mfma_f32_16x16x32_bf16 v[14:17], v[150:153], v[216:219], v[14:17]
	v_mfma_f32_16x16x32_bf16 v[2:5], v[158:161], v[216:219], v[2:5]
	s_barrier
	s_add_i32 s53, s53, 2
	s_add_u32 s40, s40, 0x100
	s_addc_u32 s41, s41, 0
	s_add_u32 s45, s45, 0x100
	s_addc_u32 s52, s52, 0
	s_cmp_gt_u32 s53, 59
	s_cbranch_scc0 .LBB0_1127
	ds_read_b128 v[130:133], v203
	ds_read_b128 v[134:137], v203 offset:1024
	ds_read_b128 v[138:141], v203 offset:2048
	ds_read_b128 v[142:145], v203 offset:3072
	ds_read_b128 v[146:149], v205
	ds_read_b128 v[150:153], v205 offset:1024
	ds_read_b128 v[154:157], v205 offset:2048
	ds_read_b128 v[158:161], v205 offset:3072
	s_add_u32 s34, s40, 0xfff00080
	s_addc_u32 s35, s41, -1
	s_cmp_eq_u32 s53, 60
	s_cselect_b32 s35, s25, s35
	s_cselect_b32 s34, s26, s34
	s_cselect_b32 s43, s23, s52
	s_cselect_b32 s42, s27, s45
	s_add_i32 m0, s47, 0xc000
	ds_read_b128 v[162:165], v207
	ds_read_b128 v[166:169], v207 offset:1024
	ds_read_b128 v[170:173], v207 offset:2048
	ds_read_b128 v[174:177], v207 offset:3072
	ds_read_b128 v[196:199], v207 offset:4096
	ds_read_b128 v[208:211], v207 offset:5120
	ds_read_b128 v[212:215], v207 offset:6144
	ds_read_b128 v[216:219], v207 offset:7168
	global_load_lds_dwordx4 v188, s[40:41]
	s_add_i32 m0, s47, 0xe000
	s_nop 0
	global_load_lds_dwordx4 v190, s[40:41]
	v_readlane_b32 s98, v254, 12
	v_readlane_b32 s99, v254, 13
	v_readlane_b32 s100, v254, 14
	v_readlane_b32 s101, v254, 15
	v_readfirstlane_b32 s73, v0
	v_lshlrev_b32_e32 v200, 1, v0
	v_and_b32_e32 v201, 3, v0
	v_and_b32_e32 v200, 24, v200
	s_lshl_b32 s74, s44, 7
	v_or3_b32 v200, v201, v200, s74
	s_lshr_b32 s74, s73, 1
	s_and_b32 s74, s74, 0x60
	v_or_b32_e32 v200, s74, v200
	v_lshlrev_b32_e32 v204, 2, v200
	v_lshrrev_b32_e32 v202, 1, v0
	v_and_b32_e32 v202, 24, v202
	v_lshlrev_b32_e32 v200, 15, v200
	v_lshl_add_u32 v200, v202, 1, v200
	s_lshl_b32 s74, s6, 9
	v_add_u32_e32 v200, s74, v200
	v_add_u32_e32 v201, 0x20000, v200
	v_and_b32_e32 v206, 0x100, v0
	v_and_b32_e32 v202, 15, v0
	v_lshlrev_b32_e32 v206, 6, v206
	v_lshl_or_b32 v206, v202, 8, v206
	v_and_b32_e32 v202, 0xf0, v0
	v_or_b32_e32 v206, v206, v202
	global_load_dword v179, v204, s[98:99]
	global_load_dword v181, v204, s[98:99] offset:16
	global_load_dword v183, v204, s[100:101]
	global_load_dword v185, v204, s[100:101] offset:16
	global_load_dwordx4 v[192:195], v200, s[50:51]
	global_load_dwordx4 v[222:225], v201, s[50:51]
	global_load_dwordx4 v[226:229], v200, s[50:51] offset:64
	global_load_dwordx4 v[234:237], v200, s[50:51] offset:128
	global_load_dwordx4 v[238:241], v200, s[50:51] offset:192
	global_load_dwordx4 v[242:245], v201, s[50:51] offset:64
	global_load_dwordx4 v[246:249], v201, s[50:51] offset:128
	global_load_dwordx4 v[250:253], v201, s[50:51] offset:192
	s_mul_hi_i32 s74, s44, 0x2aaaaaab
	s_lshl_b32 s74, s74, 15
	s_add_u32 s98, s62, s74
	s_addc_u32 s99, s63, 0
	s_mov_b32 s100, 0x20800
	s_mov_b32 s101, 0x24000
	s_bitcmp1_b32 s73, 8
	s_cselect_b32 s100, s101, s100
	s_and_b32 s74, s73, 0xc0
	s_lshl_b32 s74, s74, 4
	s_add_i32 s100, s100, s74
	s_add_u32 s98, s98, 0x1000
	s_addc_u32 s99, s99, 0
	s_add_i32 m0, s100, 0x0
	s_nop 0
	global_load_lds_dwordx4 v206, s[98:99]
	s_add_u32 s98, s98, 0x1000
	s_addc_u32 s99, s99, 0
	s_add_i32 m0, s100, 0x1000
	s_nop 0
	global_load_lds_dwordx4 v206, s[98:99]
	s_add_u32 s98, s98, 0x1000
	s_addc_u32 s99, s99, 0
	s_add_i32 m0, s100, 0x2000
	s_nop 0
	global_load_lds_dwordx4 v206, s[98:99]
	s_lshl_b32 s74, s6, 11
	s_add_u32 s98, s8, s74
	s_addc_u32 s99, s9, 0
	v_and_b32_e32 v202, 0x7f, v0
	v_lshlrev_b32_e32 v202, 4, v202
	global_load_dwordx4 v[230:233], v202, s[98:99]
	s_waitcnt vmcnt(24)
	s_waitcnt lgkmcnt(0)
	s_barrier
; #define PG8_STAGE(bufoff, gbase, voff) do { _Pragma("unroll") for (int _i = 0; _i < 2; ++_i) \
;         __builtin_amdgcn_global_load_lds((const unsigned*)((const char*)(gbase) + (voff)[_i]), (PG8_LAS unsigned*)(lds + (bufoff) + ldsw + _i * 8192), 16, 0, 0); } while (0)
; #define PG8_LDA(dst, b, h) do { _Pragma("unroll") for (int m = 0; m < 4; ++m) _Pragma("unroll") for (int k = 0; k < 2; ++k) dst[m][k] = *(const PG8_LAS bf16x8*)(lds + PG8_SA(b, h) + aoff + m * 2048 + k * 1024); } while (0)
; #define PG8_MMA(ai, bj, At, Bt) do { __builtin_amdgcn_s_setprio(1); _Pragma("unroll") for (int m = 0; m < 4; ++m) _Pragma("unroll") for (int n = 0; n < 2; ++n) _Pragma("unroll") for (int k = 0; k < 2; ++k) \
;         acc[ai][bj][m][n] = __builtin_amdgcn_mfma_f32_16x16x32_bf16(Bt[n][k], At[m][k], acc[ai][bj][m][n], 0, 0, 0); __builtin_amdgcn_s_setprio(0); } while (0)
; #define PG8_WAIT_V(n) asm volatile("s_waitcnt vmcnt(" #n ")" ::: "memory")
; #define PG8_WAIT_L(n) asm volatile("s_waitcnt lgkmcnt(" #n ")" ::: "memory")
; #define PG8_BAR __builtin_amdgcn_s_barrier()
; #define PG8_SCHED __builtin_amdgcn_sched_barrier(0)
; template <class Epi, class Sched, bool ALIGN_EPI = false, bool SP2 = false>
; __device__ __forceinline__ void gemm_phase(PG8_LAS unsigned char* lds, const Gemm g, const Sched& S, const Epi& E) {
;     ...
;             PG8_WAIT_V(8); PG8_WAIT_L(0); PG8_BAR; PG8_MMA(0, 0, At, B0); PG8_MMA(0, 1, At, B1); PG8_BAR; PG8_SCHED;
;             PG8_LDA(At, 0, 1); PG8_STAGE(PG8_SB(0, 0), b2, voffB); PG8_STAGE(PG8_SB(0, 1), b2 + hstepB, voffB); PG8_STAGE(PG8_SA(0, 0), a2, voffA);
;             PG8_WAIT_V(8); PG8_WAIT_L(0); PG8_BAR; PG8_MMA(1, 0, At, B0); PG8_MMA(1, 1, At, B1); PG8_BAR; PG8_SCHED;
	s_waitcnt lgkmcnt(0)
	v_mfma_f32_16x16x32_bf16 v[122:125], v[130:133], v[162:165], v[122:125]
	v_mfma_f32_16x16x32_bf16 v[118:121], v[138:141], v[162:165], v[118:121]
	v_mfma_f32_16x16x32_bf16 v[106:109], v[130:133], v[170:173], v[106:109]
	v_mfma_f32_16x16x32_bf16 v[102:105], v[138:141], v[170:173], v[102:105]
	v_mfma_f32_16x16x32_bf16 v[90:93], v[130:133], v[196:199], v[90:93]
	v_mfma_f32_16x16x32_bf16 v[86:89], v[138:141], v[196:199], v[86:89]
	v_mfma_f32_16x16x32_bf16 v[74:77], v[130:133], v[212:215], v[74:77]
	v_mfma_f32_16x16x32_bf16 v[70:73], v[138:141], v[212:215], v[70:73]
	v_mfma_f32_16x16x32_bf16 v[122:125], v[134:137], v[166:169], v[122:125]
	v_mfma_f32_16x16x32_bf16 v[118:121], v[142:145], v[166:169], v[118:121]
	v_mfma_f32_16x16x32_bf16 v[106:109], v[134:137], v[174:177], v[106:109]
	v_mfma_f32_16x16x32_bf16 v[102:105], v[142:145], v[174:177], v[102:105]
	v_mfma_f32_16x16x32_bf16 v[90:93], v[134:137], v[208:211], v[90:93]
	v_mfma_f32_16x16x32_bf16 v[86:89], v[142:145], v[208:211], v[86:89]
	v_mfma_f32_16x16x32_bf16 v[74:77], v[134:137], v[216:219], v[74:77]
	v_mfma_f32_16x16x32_bf16 v[70:73], v[142:145], v[216:219], v[70:73]
	v_mfma_f32_16x16x32_bf16 v[126:129], v[146:149], v[162:165], v[126:129]
	v_mfma_f32_16x16x32_bf16 v[114:117], v[154:157], v[162:165], v[114:117]
	v_mfma_f32_16x16x32_bf16 v[110:113], v[146:149], v[170:173], v[110:113]
	v_mfma_f32_16x16x32_bf16 v[98:101], v[154:157], v[170:173], v[98:101]
	v_mfma_f32_16x16x32_bf16 v[94:97], v[146:149], v[196:199], v[94:97]
	v_mfma_f32_16x16x32_bf16 v[82:85], v[154:157], v[196:199], v[82:85]
	v_mfma_f32_16x16x32_bf16 v[78:81], v[146:149], v[212:215], v[78:81]
	v_mfma_f32_16x16x32_bf16 v[66:69], v[154:157], v[212:215], v[66:69]
	v_mfma_f32_16x16x32_bf16 v[126:129], v[150:153], v[166:169], v[126:129]
	v_mfma_f32_16x16x32_bf16 v[114:117], v[158:161], v[166:169], v[114:117]
	v_mfma_f32_16x16x32_bf16 v[110:113], v[150:153], v[174:177], v[110:113]
	v_mfma_f32_16x16x32_bf16 v[98:101], v[158:161], v[174:177], v[98:101]
	v_mfma_f32_16x16x32_bf16 v[94:97], v[150:153], v[208:211], v[94:97]
	v_mfma_f32_16x16x32_bf16 v[82:85], v[158:161], v[208:211], v[82:85]
	v_mfma_f32_16x16x32_bf16 v[78:81], v[150:153], v[216:219], v[78:81]
	v_mfma_f32_16x16x32_bf16 v[66:69], v[158:161], v[216:219], v[66:69]
	s_barrier
	s_add_i32 s73, s68, s17
	s_add_u32 s98, s42, 0x80
	s_addc_u32 s99, s43, 0
	s_add_u32 s100, s34, 0x80
	s_addc_u32 s101, s35, 0
	s_mov_b32 m0, s73
	ds_read_b128 v[162:165], v207 offset:16384
	ds_read_b128 v[166:169], v207 offset:17408
	ds_read_b128 v[170:173], v207 offset:18432
	ds_read_b128 v[174:177], v207 offset:19456
	ds_read_b128 v[196:199], v207 offset:20480
	ds_read_b128 v[208:211], v207 offset:21504
	ds_read_b128 v[212:215], v207 offset:22528
	ds_read_b128 v[216:219], v207 offset:23552
	global_load_lds_dwordx4 v182, s[42:43]
	s_add_i32 m0, s73, 0x2000
	s_add_u32 s74, s42, 0x100000
	s_addc_u32 s75, s43, 0
	s_add_i32 s73, s69, s17
	global_load_lds_dwordx4 v178, s[42:43]
	s_mov_b32 m0, s73
	s_nop 0
	global_load_lds_dwordx4 v182, s[74:75]
	s_add_i32 m0, s73, 0x2000
	s_nop 0
	global_load_lds_dwordx4 v178, s[74:75]
	s_mov_b32 m0, s47
	s_nop 0
	global_load_lds_dwordx4 v184, s[34:35]
	s_mov_b32 m0, s48
	s_nop 0
	global_load_lds_dwordx4 v180, s[34:35]
	s_waitcnt vmcnt(24)
	s_waitcnt lgkmcnt(0)
	s_barrier
	s_waitcnt lgkmcnt(0)
	v_mfma_f32_16x16x32_bf16 v[58:61], v[130:133], v[162:165], v[58:61]
	v_mfma_f32_16x16x32_bf16 v[54:57], v[138:141], v[162:165], v[54:57]
	v_mfma_f32_16x16x32_bf16 v[42:45], v[130:133], v[170:173], v[42:45]
	v_mfma_f32_16x16x32_bf16 v[38:41], v[138:141], v[170:173], v[38:41]
	v_mfma_f32_16x16x32_bf16 v[26:29], v[130:133], v[196:199], v[26:29]
	v_mfma_f32_16x16x32_bf16 v[22:25], v[138:141], v[196:199], v[22:25]
	v_mfma_f32_16x16x32_bf16 v[10:13], v[130:133], v[212:215], v[10:13]
	v_mfma_f32_16x16x32_bf16 v[6:9], v[138:141], v[212:215], v[6:9]
	v_mfma_f32_16x16x32_bf16 v[58:61], v[134:137], v[166:169], v[58:61]
	v_mfma_f32_16x16x32_bf16 v[54:57], v[142:145], v[166:169], v[54:57]
	v_mfma_f32_16x16x32_bf16 v[42:45], v[134:137], v[174:177], v[42:45]
	v_mfma_f32_16x16x32_bf16 v[38:41], v[142:145], v[174:177], v[38:41]
	v_mfma_f32_16x16x32_bf16 v[26:29], v[134:137], v[208:211], v[26:29]
	v_mfma_f32_16x16x32_bf16 v[22:25], v[142:145], v[208:211], v[22:25]
	v_mfma_f32_16x16x32_bf16 v[10:13], v[134:137], v[216:219], v[10:13]
	v_mfma_f32_16x16x32_bf16 v[6:9], v[142:145], v[216:219], v[6:9]
	v_mfma_f32_16x16x32_bf16 v[62:65], v[146:149], v[162:165], v[62:65]
	v_mfma_f32_16x16x32_bf16 v[50:53], v[154:157], v[162:165], v[50:53]
	v_mfma_f32_16x16x32_bf16 v[46:49], v[146:149], v[170:173], v[46:49]
	v_mfma_f32_16x16x32_bf16 v[34:37], v[154:157], v[170:173], v[34:37]
	v_mfma_f32_16x16x32_bf16 v[30:33], v[146:149], v[196:199], v[30:33]
	v_mfma_f32_16x16x32_bf16 v[18:21], v[154:157], v[196:199], v[18:21]
	v_mfma_f32_16x16x32_bf16 v[14:17], v[146:149], v[212:215], v[14:17]
	v_mfma_f32_16x16x32_bf16 v[2:5], v[154:157], v[212:215], v[2:5]
	v_mfma_f32_16x16x32_bf16 v[62:65], v[150:153], v[166:169], v[62:65]
	v_mfma_f32_16x16x32_bf16 v[50:53], v[158:161], v[166:169], v[50:53]
	v_mfma_f32_16x16x32_bf16 v[46:49], v[150:153], v[174:177], v[46:49]
	v_mfma_f32_16x16x32_bf16 v[34:37], v[158:161], v[174:177], v[34:37]
	v_mfma_f32_16x16x32_bf16 v[30:33], v[150:153], v[208:211], v[30:33]
	v_mfma_f32_16x16x32_bf16 v[18:21], v[158:161], v[208:211], v[18:21]
	v_mfma_f32_16x16x32_bf16 v[14:17], v[150:153], v[216:219], v[14:17]
	v_mfma_f32_16x16x32_bf16 v[2:5], v[158:161], v[216:219], v[2:5]
	s_barrier
; #define PG8_STAGE(bufoff, gbase, voff) do { _Pragma("unroll") for (int _i = 0; _i < 2; ++_i) \
;         __builtin_amdgcn_global_load_lds((const unsigned*)((const char*)(gbase) + (voff)[_i]), (PG8_LAS unsigned*)(lds + (bufoff) + ldsw + _i * 8192), 16, 0, 0); } while (0)
; #define PG8_LDA(dst, b, h) do { _Pragma("unroll") for (int m = 0; m < 4; ++m) _Pragma("unroll") for (int k = 0; k < 2; ++k) dst[m][k] = *(const PG8_LAS bf16x8*)(lds + PG8_SA(b, h) + aoff + m * 2048 + k * 1024); } while (0)
; #define PG8_LDB(dst, b, h) do { _Pragma("unroll") for (int n = 0; n < 2; ++n) _Pragma("unroll") for (int k = 0; k < 2; ++k) dst[n][k] = *(const PG8_LAS bf16x8*)(lds + PG8_SB(b, h) + boff + n * 2048 + k * 1024); } while (0)
; #define PG8_MMA(ai, bj, At, Bt) do { __builtin_amdgcn_s_setprio(1); _Pragma("unroll") for (int m = 0; m < 4; ++m) _Pragma("unroll") for (int n = 0; n < 2; ++n) _Pragma("unroll") for (int k = 0; k < 2; ++k) \
;         acc[ai][bj][m][n] = __builtin_amdgcn_mfma_f32_16x16x32_bf16(Bt[n][k], At[m][k], acc[ai][bj][m][n], 0, 0, 0); __builtin_amdgcn_s_setprio(0); } while (0)
; #define PG8_WAIT_V(n) asm volatile("s_waitcnt vmcnt(" #n ")" ::: "memory")
; #define PG8_WAIT_L(n) asm volatile("s_waitcnt lgkmcnt(" #n ")" ::: "memory")
; #define PG8_BAR __builtin_amdgcn_s_barrier()
; #define PG8_SCHED __builtin_amdgcn_sched_barrier(0)
; template <class Epi, class Sched, bool ALIGN_EPI = false, bool SP2 = false>
; __device__ __forceinline__ void gemm_phase(PG8_LAS unsigned char* lds, const Gemm g, const Sched& S, const Epi& E) {
;     ...
;             PG8_LDA(At, 0, 1); PG8_STAGE(PG8_SB(0, 0), b2, voffB); PG8_STAGE(PG8_SB(0, 1), b2 + hstepB, voffB); PG8_STAGE(PG8_SA(0, 0), a2, voffA);
;             PG8_WAIT_V(8); PG8_WAIT_L(0); PG8_BAR; PG8_MMA(1, 0, At, B0); PG8_MMA(1, 1, At, B1); PG8_BAR; PG8_SCHED;
;             PG8_LDB(B0, 1, 0); PG8_LDB(B1, 1, 1); PG8_SCHED; PG8_LDA(At, 1, 0); PG8_STAGE(PG8_SA(0, 1), a2 + hstepA, voffA);
;             PG8_WAIT_V(8); PG8_WAIT_L(0); PG8_BAR; PG8_MMA(0, 0, At, B0); PG8_MMA(0, 1, At, B1); PG8_BAR; PG8_SCHED;
;             PG8_LDA(At, 1, 1); PG8_STAGE(PG8_SB(1, 0), b3, voffB); PG8_STAGE(PG8_SB(1, 1), b3 + hstepB, voffB); PG8_STAGE(PG8_SA(1, 0), a3, voffA);
;             PG8_WAIT_V(8); PG8_WAIT_L(0); PG8_BAR; PG8_MMA(1, 0, At, B0); PG8_MMA(1, 1, At, B1); PG8_BAR; PG8_SCHED;
	s_add_i32 s73, 0, 0x18000
	s_add_i32 s74, 0, 0x1c000
	v_add_u32_e32 v142, s73, v1
	v_add_u32_e32 v158, s74, v1
	ds_read_b128 v[130:133], v142
	ds_read_b128 v[134:137], v142 offset:1024
	ds_read_b128 v[138:141], v142 offset:2048
	ds_read_b128 v[142:145], v142 offset:3072
	ds_read_b128 v[146:149], v158
	ds_read_b128 v[150:153], v158 offset:1024
	ds_read_b128 v[154:157], v158 offset:2048
	ds_read_b128 v[158:161], v158 offset:3072
	s_add_u32 s34, s34, 0x100000
	s_addc_u32 s35, s35, 0
	s_mov_b32 m0, s49
	ds_read_b128 v[162:165], v207 offset:32768
	ds_read_b128 v[166:169], v207 offset:33792
	ds_read_b128 v[170:173], v207 offset:34816
	ds_read_b128 v[174:177], v207 offset:35840
	ds_read_b128 v[196:199], v207 offset:36864
	ds_read_b128 v[208:211], v207 offset:37888
	ds_read_b128 v[212:215], v207 offset:38912
	ds_read_b128 v[216:219], v207 offset:39936
	global_load_lds_dwordx4 v184, s[34:35]
	s_mov_b32 m0, s60
	s_nop 0
	global_load_lds_dwordx4 v180, s[34:35]
	s_waitcnt vmcnt(24)
	s_waitcnt lgkmcnt(0)
	s_barrier
	s_waitcnt lgkmcnt(0)
	v_mfma_f32_16x16x32_bf16 v[122:125], v[130:133], v[162:165], v[122:125]
	v_mfma_f32_16x16x32_bf16 v[118:121], v[138:141], v[162:165], v[118:121]
	v_mfma_f32_16x16x32_bf16 v[106:109], v[130:133], v[170:173], v[106:109]
	v_mfma_f32_16x16x32_bf16 v[102:105], v[138:141], v[170:173], v[102:105]
	v_mfma_f32_16x16x32_bf16 v[90:93], v[130:133], v[196:199], v[90:93]
	v_mfma_f32_16x16x32_bf16 v[86:89], v[138:141], v[196:199], v[86:89]
	v_mfma_f32_16x16x32_bf16 v[74:77], v[130:133], v[212:215], v[74:77]
	v_mfma_f32_16x16x32_bf16 v[70:73], v[138:141], v[212:215], v[70:73]
	v_mfma_f32_16x16x32_bf16 v[122:125], v[134:137], v[166:169], v[122:125]
	v_mfma_f32_16x16x32_bf16 v[118:121], v[142:145], v[166:169], v[118:121]
	v_mfma_f32_16x16x32_bf16 v[106:109], v[134:137], v[174:177], v[106:109]
	v_mfma_f32_16x16x32_bf16 v[102:105], v[142:145], v[174:177], v[102:105]
	v_mfma_f32_16x16x32_bf16 v[90:93], v[134:137], v[208:211], v[90:93]
	v_mfma_f32_16x16x32_bf16 v[86:89], v[142:145], v[208:211], v[86:89]
	v_mfma_f32_16x16x32_bf16 v[74:77], v[134:137], v[216:219], v[74:77]
	v_mfma_f32_16x16x32_bf16 v[70:73], v[142:145], v[216:219], v[70:73]
	v_mfma_f32_16x16x32_bf16 v[126:129], v[146:149], v[162:165], v[126:129]
	v_mfma_f32_16x16x32_bf16 v[114:117], v[154:157], v[162:165], v[114:117]
	v_mfma_f32_16x16x32_bf16 v[110:113], v[146:149], v[170:173], v[110:113]
	v_mfma_f32_16x16x32_bf16 v[98:101], v[154:157], v[170:173], v[98:101]
	v_mfma_f32_16x16x32_bf16 v[94:97], v[146:149], v[196:199], v[94:97]
	v_mfma_f32_16x16x32_bf16 v[82:85], v[154:157], v[196:199], v[82:85]
	v_mfma_f32_16x16x32_bf16 v[78:81], v[146:149], v[212:215], v[78:81]
	v_mfma_f32_16x16x32_bf16 v[66:69], v[154:157], v[212:215], v[66:69]
	v_mfma_f32_16x16x32_bf16 v[126:129], v[150:153], v[166:169], v[126:129]
	v_mfma_f32_16x16x32_bf16 v[114:117], v[158:161], v[166:169], v[114:117]
	v_mfma_f32_16x16x32_bf16 v[110:113], v[150:153], v[174:177], v[110:113]
	v_mfma_f32_16x16x32_bf16 v[98:101], v[158:161], v[174:177], v[98:101]
	v_mfma_f32_16x16x32_bf16 v[94:97], v[150:153], v[208:211], v[94:97]
	v_mfma_f32_16x16x32_bf16 v[82:85], v[158:161], v[208:211], v[82:85]
	v_mfma_f32_16x16x32_bf16 v[78:81], v[150:153], v[216:219], v[78:81]
	v_mfma_f32_16x16x32_bf16 v[66:69], v[158:161], v[216:219], v[66:69]
	s_barrier
	s_add_i32 s34, s73, s17
	s_mov_b32 m0, s34
	ds_read_b128 v[162:165], v207 offset:49152
	ds_read_b128 v[166:169], v207 offset:50176
	ds_read_b128 v[170:173], v207 offset:51200
	ds_read_b128 v[174:177], v207 offset:52224
	ds_read_b128 v[196:199], v207 offset:53248
	ds_read_b128 v[208:211], v207 offset:54272
	ds_read_b128 v[212:215], v207 offset:55296
	ds_read_b128 v[216:219], v207 offset:56320
	global_load_lds_dwordx4 v182, s[98:99]
	s_add_i32 m0, s34, 0x2000
	s_add_u32 s34, s42, 0x100080
	s_addc_u32 s35, s43, 0
	s_add_i32 s42, s74, s17
	global_load_lds_dwordx4 v178, s[98:99]
	s_mov_b32 m0, s42
	s_nop 0
	global_load_lds_dwordx4 v182, s[34:35]
	s_add_i32 m0, s42, 0x2000
	s_nop 0
	global_load_lds_dwordx4 v178, s[34:35]
	s_mov_b32 m0, s64
	s_nop 0
	global_load_lds_dwordx4 v184, s[100:101]
	s_mov_b32 m0, s65
	s_nop 0
	global_load_lds_dwordx4 v180, s[100:101]
	s_waitcnt vmcnt(8)
	s_waitcnt lgkmcnt(0)
	s_barrier
	s_waitcnt lgkmcnt(0)
	v_mfma_f32_16x16x32_bf16 v[58:61], v[130:133], v[162:165], v[58:61]
	v_mfma_f32_16x16x32_bf16 v[54:57], v[138:141], v[162:165], v[54:57]
	v_mfma_f32_16x16x32_bf16 v[42:45], v[130:133], v[170:173], v[42:45]
	v_mfma_f32_16x16x32_bf16 v[38:41], v[138:141], v[170:173], v[38:41]
	v_mfma_f32_16x16x32_bf16 v[26:29], v[130:133], v[196:199], v[26:29]
	v_mfma_f32_16x16x32_bf16 v[22:25], v[138:141], v[196:199], v[22:25]
	v_mfma_f32_16x16x32_bf16 v[10:13], v[130:133], v[212:215], v[10:13]
	v_mfma_f32_16x16x32_bf16 v[6:9], v[138:141], v[212:215], v[6:9]
	v_mfma_f32_16x16x32_bf16 v[58:61], v[134:137], v[166:169], v[58:61]
	v_mfma_f32_16x16x32_bf16 v[54:57], v[142:145], v[166:169], v[54:57]
	v_mfma_f32_16x16x32_bf16 v[42:45], v[134:137], v[174:177], v[42:45]
	v_mfma_f32_16x16x32_bf16 v[38:41], v[142:145], v[174:177], v[38:41]
	v_mfma_f32_16x16x32_bf16 v[26:29], v[134:137], v[208:211], v[26:29]
	v_mfma_f32_16x16x32_bf16 v[22:25], v[142:145], v[208:211], v[22:25]
	v_mfma_f32_16x16x32_bf16 v[10:13], v[134:137], v[216:219], v[10:13]
	v_mfma_f32_16x16x32_bf16 v[6:9], v[142:145], v[216:219], v[6:9]
	v_mfma_f32_16x16x32_bf16 v[62:65], v[146:149], v[162:165], v[62:65]
	v_mfma_f32_16x16x32_bf16 v[50:53], v[154:157], v[162:165], v[50:53]
	v_mfma_f32_16x16x32_bf16 v[46:49], v[146:149], v[170:173], v[46:49]
	v_mfma_f32_16x16x32_bf16 v[34:37], v[154:157], v[170:173], v[34:37]
	v_mfma_f32_16x16x32_bf16 v[30:33], v[146:149], v[196:199], v[30:33]
	v_mfma_f32_16x16x32_bf16 v[18:21], v[154:157], v[196:199], v[18:21]
	v_mfma_f32_16x16x32_bf16 v[14:17], v[146:149], v[212:215], v[14:17]
	v_mfma_f32_16x16x32_bf16 v[2:5], v[154:157], v[212:215], v[2:5]
	v_mfma_f32_16x16x32_bf16 v[62:65], v[150:153], v[166:169], v[62:65]
	v_mfma_f32_16x16x32_bf16 v[50:53], v[158:161], v[166:169], v[50:53]
	v_mfma_f32_16x16x32_bf16 v[46:49], v[150:153], v[174:177], v[46:49]
	v_mfma_f32_16x16x32_bf16 v[34:37], v[158:161], v[174:177], v[34:37]
	v_mfma_f32_16x16x32_bf16 v[30:33], v[150:153], v[208:211], v[30:33]
	v_mfma_f32_16x16x32_bf16 v[18:21], v[158:161], v[208:211], v[18:21]
	v_mfma_f32_16x16x32_bf16 v[14:17], v[150:153], v[216:219], v[14:17]
	v_mfma_f32_16x16x32_bf16 v[2:5], v[158:161], v[216:219], v[2:5]
	s_barrier
	s_add_i32 s53, s53, 2
	s_add_u32 s40, s40, 0x100
	s_addc_u32 s41, s41, 0
	s_add_u32 s45, s45, 0x100
	s_addc_u32 s52, s52, 0
	s_setprio 0
	s_and_b64 vcc, exec, s[14:15]
	s_cbranch_vccz .LBB0_1130
	s_barrier
